# class-major dilation-16 jobs: query-tile index rotated across a wave's four jobs so every wave runs 10 tiles instead of 4..16
# baseline (speedup 1.0000x reference)
; DI int pi_row(int r) { return (r & 3) | (((r >> 3) & 1) << 2) | (((r >> 2) & 1) << 3) | (r & 16); }
; DI void load_lut(float* lut, const float* glut, int col, int lane) {
;     ...
;     f32x4 t[8];
; #pragma unroll
;     for (int k = 0; k < 8; ++k) t[k] = *(const f32x4*)(glut + (size_t)col * 2048 + k * 256 + lane * 4);
; #pragma unroll
;     for (int k = 0; k < 8; ++k) *(f32x4*)(lut + k * 256 + lane * 4) = t[k];
; DI void g2_job(const Args& a, unsigned char* wsh, LAS unsigned char* wl, int b, int slot, int cls, int it, const int tid) {
;     ...
;     float* lut = (float*)(wsh + 8192);
;     const int tok0 = b * SEQ;
;     const int d00 = 32 * it + r - 8 * h;
;     AttnCtx c; c.wl = wl; c.lut = lut; c.krs = 16;
; #pragma unroll
;     for (int j = 0; j < 4; ++j) {
;         const int rk = 8 * j + (lane >> 3), ck = (lane & 7) ^ ((rk >> 1) & 7);
;         c.koff[j] = (unsigned)(pi_row(rk) * 16 * RM_LD + ck * 8) * 2u;
;         const int rv = 16 * j + (lane >> 2), cv = (lane & 3) ^ ((rv >> 2) & 3);
;         c.voff[j] = (unsigned)(rv * MTOK + cv * 8) * 2u;
;         c.kfo[j] = r * 128 + (((2 * j + h) ^ ((r >> 1) & 7)) * 16);
;     }
; #pragma unroll
;     for (int mt = 0; mt < 2; ++mt)
; #pragma unroll
;         for (int s = 0; s < 2; ++s) c.vfo[mt][s] = (32 * mt + r) * 64 + (((2 * s + h) ^ ((r >> 2) & 3)) * 16);
;     AttnSt st; st.m = NEGF; st.l = 0.f;
; #pragma unroll
;     for (int i = 0; i < 16; ++i) { st.o0[i] = 0.f; st.o1[i] = 0.f; }
;     load_lut(lut, glut, 6 + 2 * 4 + slot, lane);
;     const int tq = tok0 + cls + 16 * (32 * it + r);
;     bf16x8 qf[4];
;     const bf16_t* qp = prm + (size_t)tq * RM_LD + C_BQ + (2 * 4 + slot) * 64 + 8 * h;
; #pragma unroll
;     for (int ks = 0; ks < 4; ++ks) qf[ks] = *(const bf16x8*)(qp + 16 * ks);
;     c.kg = prm + (size_t)(tok0 + cls) * RM_LD + C_BK + slot * 64;
;     c.vg = vt16 + (size_t)(slot * 64) * MTOK + tok0 + cls * 128;
;     attn_range<4>(c, qf, 0, it, 0, d00, st, nullptr, 0, 0, 0, false);
.LBB0_520:
	s_or_b64 exec, exec, s[0:1]
	v_readlane_b32 s0, v251, 9
	s_add_i32 s40, s40, s0
	v_readlane_b32 s0, v254, 2
	s_add_i32 s42, s42, s80
	s_add_i32 s41, s41, s0
	s_add_i32 s8, s8, 1
	s_and_b32 s8, s8, 3
	s_cmpk_lt_i32 s42, 0x400
	s_cbranch_scc0 .LBB0_531
.LBB0_521:
	s_add_i32 s9, s8, 1
	v_and_b32_e32 v3, 31, v210
	v_lshrrev_b32_e32 v151, 2, v210
	v_lshl_or_b32 v3, s8, 5, v3
	v_and_b32_e32 v151, 8, v151
	s_add_i32 s98, s7, 0x1a40
	v_sub_u32_e32 v151, v3, v151
	v_lshlrev_b32_e32 v150, 4, v3
	v_lshl_add_u32 v152, v151, 6, s98
	s_lshl_b32 s0, s40, 17
	s_and_b32 s2, s0, 0x1800000
	s_and_b32 s0, s41, 0xfffff800
	s_bfe_u32 s43, s40, 0x40002
	s_ashr_i32 s1, s0, 31
	s_lshl_b32 s44, s43, 8
	s_lshl_b64 s[4:5], s[0:1], 1
	s_or_b32 s1, s4, s44
	s_add_u32 s4, s1, s2
	s_addc_u32 s5, s5, 0
	s_or_b32 s0, s0, s43
	s_lshl_b32 s2, s40, 1
	s_mul_hi_i32 s1, s0, 0x1600
	s_mulk_i32 s0, 0x1600
	s_and_b32 s2, s2, 0x180
	s_or_b32 s0, s0, s2
	v_lshl_add_u64 v[138:139], s[0:1], 0, v[120:121]
	v_lshl_add_u64 v[140:141], s[0:1], 0, v[122:123]
	v_lshl_add_u64 v[142:143], s[0:1], 0, v[124:125]
	v_lshl_add_u64 v[144:145], s[0:1], 0, v[126:127]
	s_lshl_b32 s0, s42, 3
	s_add_i32 s0, s0, s6
	s_bfe_u32 s43, s0, 0x20006
	s_bfe_u32 s45, s0, 0x40002
	s_lshl_b32 s0, s0, 3
	s_and_b32 s0, s0, 0xfffff800
	s_lshl_b32 s1, s43, 13
	v_lshl_add_u64 v[130:131], s[4:5], 0, v[100:101]
	v_lshl_add_u64 v[132:133], s[4:5], 0, v[114:115]
	v_lshl_add_u64 v[134:135], s[4:5], 0, v[116:117]
	v_lshl_add_u64 v[136:137], s[4:5], 0, v[118:119]
	s_add_u32 s4, s92, s1
	s_addc_u32 s5, s93, 0
	v_lshl_add_u64 v[2:3], s[4:5], 0, v[0:1]
	s_mov_b32 s1, 0x471d000
	s_mov_b64 s[4:5], 0x471c000
	v_add_co_u32_e32 v30, vcc, s1, v2
	v_lshl_add_u64 v[14:15], v[2:3], 0, s[4:5]
	s_nop 0
	v_addc_co_u32_e32 v31, vcc, 0, v3, vcc
	global_load_dwordx4 v[2:5], v[30:31], off offset:-4096
	global_load_dwordx4 v[6:9], v[14:15], off offset:1024
	global_load_dwordx4 v[10:13], v[14:15], off offset:2048
	s_nop 0
	global_load_dwordx4 v[14:17], v[14:15], off offset:3072
	s_nop 0
	global_load_dwordx4 v[18:21], v[30:31], off
	global_load_dwordx4 v[22:25], v[30:31], off offset:1024
	global_load_dwordx4 v[26:29], v[30:31], off offset:2048
	s_nop 0
	global_load_dwordx4 v[30:33], v[30:31], off offset:3072
	v_readlane_b32 s46, v254, 55
	s_or_b32 s1, s45, s0
	v_readlane_b32 s47, v254, 56
	v_or_b32_e32 v146, s1, v150
	s_movk_i32 s2, 0x1600
	v_mov_b32_e32 v99, v1
	s_mov_b32 m0, s7
	s_mov_b32 s44, 0
	v_ashrrev_i32_e32 v147, 31, v146
	v_mov_b32_e32 v160, 0xf149f2ca
	v_mov_b32_e32 v129, v152
	v_mov_b32_e32 v159, v151
	s_waitcnt vmcnt(0)
	ds_write_b128 v149, v[2:5] offset:8192
	s_waitcnt vmcnt(6)
	ds_write_b128 v149, v[6:9] offset:9216
	s_waitcnt vmcnt(5)
	ds_write_b128 v149, v[10:13] offset:10240
	s_waitcnt vmcnt(4)
	ds_write_b128 v149, v[14:17] offset:11264
	s_waitcnt vmcnt(3)
	ds_write_b128 v149, v[18:21] offset:12288
	s_waitcnt vmcnt(2)
	ds_write_b128 v149, v[22:25] offset:13312
	s_waitcnt vmcnt(1)
	ds_write_b128 v149, v[26:29] offset:14336
	s_waitcnt vmcnt(0)
	ds_write_b128 v149, v[30:33] offset:15360
	v_mov_b64_e32 v[2:3], s[46:47]
	v_mad_i64_i32 v[2:3], s[4:5], v146, s2, v[2:3]
	s_lshl_b32 s2, s43, 7
	s_mul_hi_i32 s4, s1, 0x1600
	s_mulk_i32 s1, 0x1600
	s_add_u32 s1, s46, s1
	s_addc_u32 s5, s47, s4
	s_add_u32 s4, s1, s2
	s_addc_u32 s5, s5, 0
	s_lshl_b32 s1, s43, 23
	v_readlane_b32 s46, v251, 32
	v_lshl_add_u64 v[2:3], v[2:3], 0, s[2:3]
	v_readlane_b32 s47, v251, 33
	s_add_u32 s2, s46, s1
	s_addc_u32 s46, s47, 0
	s_ashr_i32 s1, s0, 31
	s_lshl_b64 s[0:1], s[0:1], 1
	v_lshl_add_u64 v[2:3], v[2:3], 0, v[98:99]
	s_add_u32 s0, s2, s0
	global_load_dwordx4 v[50:53], v[2:3], off offset:3072
	global_load_dwordx4 v[54:57], v[2:3], off offset:3104
	global_load_dwordx4 v[58:61], v[2:3], off offset:3136
	global_load_dwordx4 v[62:65], v[2:3], off offset:3168
	s_addc_u32 s1, s46, s1
	s_lshl_b32 s2, s45, 8
	v_lshl_add_u64 v[2:3], s[4:5], 0, v[96:97]
	s_add_u32 s0, s0, s2
	v_lshl_add_u64 v[2:3], v[2:3], 0, s[20:21]
	s_addc_u32 s1, s1, 0
	global_load_lds_dwordx4 v[2:3], off
	v_lshl_add_u64 v[2:3], s[4:5], 0, v[102:103]
	s_add_i32 s2, s7, 0x400
	v_lshl_add_u64 v[2:3], v[2:3], 0, s[20:21]
	s_mov_b32 m0, s2
	s_add_i32 s45, s7, 0x800
	global_load_lds_dwordx4 v[2:3], off
	v_lshl_add_u64 v[2:3], s[4:5], 0, v[106:107]
	v_lshl_add_u64 v[2:3], v[2:3], 0, s[20:21]
	s_mov_b32 m0, s45
	s_add_i32 s46, s7, 0x1400
	global_load_lds_dwordx4 v[2:3], off
	v_lshl_add_u64 v[2:3], s[4:5], 0, v[110:111]
	s_add_i32 s4, s7, 0xc00
	v_lshl_add_u64 v[2:3], v[2:3], 0, s[20:21]
	s_mov_b32 m0, s4
	s_add_i32 s5, s7, 0x1000
	global_load_lds_dwordx4 v[2:3], off
	v_lshl_add_u64 v[2:3], s[0:1], 0, v[94:95]
	s_mov_b32 m0, s5
	s_add_i32 s47, s7, 0x1800
	global_load_lds_dwordx4 v[2:3], off
	v_lshl_add_u64 v[2:3], s[0:1], 0, v[104:105]
	s_mov_b32 m0, s46
	v_mov_b32_e32 v16, v1
	global_load_lds_dwordx4 v[2:3], off
	v_lshl_add_u64 v[2:3], s[0:1], 0, v[108:109]
	s_mov_b32 m0, s47
	v_mov_b32_e32 v17, v1
	global_load_lds_dwordx4 v[2:3], off
	v_lshl_add_u64 v[2:3], s[0:1], 0, v[112:113]
	s_add_i32 s0, s7, 0x1c00
	s_mov_b32 m0, s0
	v_mov_b32_e32 v4, v1
	global_load_lds_dwordx4 v[2:3], off
	v_mov_b32_e32 v2, v1
	v_mov_b32_e32 v3, v1
	v_mov_b32_e32 v5, v1
	v_mov_b32_e32 v6, v1
	v_mov_b32_e32 v7, v1
	v_mov_b32_e32 v8, v1
	v_mov_b32_e32 v9, v1
	v_mov_b32_e32 v10, v1
	v_mov_b32_e32 v11, v1
	v_mov_b32_e32 v12, v1
	v_mov_b32_e32 v13, v1
	v_mov_b32_e32 v14, v1
	v_mov_b32_e32 v15, v1
	v_mov_b64_e32 v[32:33], v[16:17]
	v_mov_b32_e32 v99, 0
	v_mov_b64_e32 v[30:31], v[14:15]
	v_mov_b64_e32 v[28:29], v[12:13]
	v_mov_b64_e32 v[26:27], v[10:11]
	v_mov_b64_e32 v[24:25], v[8:9]
	v_mov_b64_e32 v[22:23], v[6:7]
	v_mov_b64_e32 v[20:21], v[4:5]
	v_mov_b64_e32 v[18:19], v[2:3]
	s_waitcnt vmcnt(0)
